# v31 + GEMM2 per-head wait: MLA head hh gates only K slice 10+hh (per-head nibble flags, cached poll)
# baseline (speedup 1.0000x reference)
.LBB0_355:
	s_and_saveexec_b64 s[2:3], s[40:41]
	s_xor_b64 s[28:29], exec, s[2:3]
	s_cbranch_execz .LBB0_154
	v_mov_b64_e32 v[0:1], s[64:65]
	global_atomic_add v[0:1], v181, off
	v_readlane_b32 s100, v185, 0
	s_sub_u32 s101, s100, 0x60
	s_cmpk_lt_u32 s101, 0xa0
	s_cbranch_scc1 .Lypart_add
	s_sub_u32 s101, s100, 0x160
	s_cmpk_lt_u32 s101, 0xa0
	s_cbranch_scc1 .Lypart_add
	s_lshr_b32 s101, s100, 2
	s_cmpk_lt_u32 s100, 0x60
	s_cbranch_scc1 .Lyhead_add
	s_sub_u32 s101, s100, 0x100
	s_cmpk_lt_u32 s101, 0x60
	s_cbranch_scc1 .Lyhead_add
	s_branch .LBB0_154

.Lyhead_add:
	s_mul_i32 s100, s101, 43
	s_lshr_b32 s100, s100, 8
	s_mul_i32 s100, s100, 6
	s_sub_u32 s101, s101, s100
	s_lshl_b32 s101, s101, 2
	s_lshl_b32 s101, 1, s101
	v_mov_b32_e32 v189, s101
	global_atomic_add v[0:1], v189, off offset:8
	s_branch .LBB0_154

.LBB0_393:
	s_and_b32 s0, s28, 1
	s_xor_b32 s29, s0, 1
	s_mul_i32 s29, s29, 0xc000
	s_add_i32 s34, s52, s29
	v_lshl_add_u64 v[94:95], v[92:93], 0, s[26:27]
	s_mul_i32 s0, s0, 0xc000
	s_add_i32 s29, s50, s29
	s_mov_b32 m0, s34
	v_lshl_add_u64 v[96:97], v[88:89], 0, s[26:27]
	s_add_i32 s0, s0, 0
	global_load_lds_dwordx4 v[94:95], off
	s_add_i32 m0, s29, 0x4000
	v_lshl_add_u64 v[98:99], v[86:87], 0, s[26:27]
	v_add_u32_e32 v80, s0, v153
	v_add_u32_e32 v139, s0, v154
	global_load_lds_dwordx4 v[96:97], off
	s_add_i32 m0, s29, 0x4400
	v_add_u32_e32 v146, v80, v151
	v_add_u32_e32 v110, v139, v151
	global_load_lds_dwordx4 v[98:99], off
	ds_read_b128 v[94:97], v146
	ds_read_b128 v[98:101], v110 offset:16384
	ds_read_b128 v[102:105], v110 offset:18432
	ds_read_b128 v[106:109], v110 offset:20480
	ds_read_b128 v[110:113], v110 offset:22528
	s_waitcnt lgkmcnt(0)
	v_mfma_f32_16x16x32_bf16 v[76:79], v[94:97], v[98:101], v[76:79]
	v_lshl_add_u64 v[140:141], v[90:91], 0, s[26:27]
	s_add_i32 s0, s29, 0x4800
	s_add_i32 m0, s34, 0x400
	v_mfma_f32_16x16x32_bf16 v[72:75], v[94:97], v[102:105], v[72:75]
	v_lshl_add_u64 v[142:143], v[82:83], 0, s[26:27]
	s_addk_i32 s29, 0x4c00
	v_lshl_add_u64 v[144:145], v[84:85], 0, s[26:27]
	v_mfma_f32_16x16x32_bf16 v[68:71], v[94:97], v[106:109], v[68:71]
	v_add_u32_e32 v80, v80, v152
	v_add_u32_e32 v139, v139, v152
	s_add_i32 s28, s28, 1
	v_mfma_f32_16x16x32_bf16 v[64:67], v[94:97], v[110:113], v[64:67]
	ds_read_b128 v[94:97], v146 offset:2048
	s_add_u32 s26, s26, 0x80
	s_addc_u32 s27, s27, 0
	s_waitcnt lgkmcnt(0)
	v_mfma_f32_16x16x32_bf16 v[60:63], v[94:97], v[98:101], v[60:63]
	s_cmpk_eq_i32 s26, 0x780
	v_mfma_f32_16x16x32_bf16 v[56:59], v[94:97], v[102:105], v[56:59]
	v_mfma_f32_16x16x32_bf16 v[52:55], v[94:97], v[106:109], v[52:55]
	v_mfma_f32_16x16x32_bf16 v[48:51], v[94:97], v[110:113], v[48:51]
	ds_read_b128 v[94:97], v146 offset:4096
	s_waitcnt lgkmcnt(0)
	v_mfma_f32_16x16x32_bf16 v[44:47], v[94:97], v[98:101], v[44:47]
	v_mfma_f32_16x16x32_bf16 v[40:43], v[94:97], v[102:105], v[40:43]
	v_mfma_f32_16x16x32_bf16 v[32:35], v[94:97], v[106:109], v[32:35]
	v_mfma_f32_16x16x32_bf16 v[24:27], v[94:97], v[110:113], v[24:27]
	ds_read_b128 v[94:97], v146 offset:6144
	global_load_lds_dwordx4 v[140:141], off
	s_mov_b32 m0, s0
	s_waitcnt lgkmcnt(0)
	v_mfma_f32_16x16x32_bf16 v[20:23], v[94:97], v[98:101], v[20:23]
	global_load_lds_dwordx4 v[142:143], off
	s_mov_b32 m0, s29
	v_mfma_f32_16x16x32_bf16 v[16:19], v[94:97], v[102:105], v[16:19]
	global_load_lds_dwordx4 v[144:145], off
	ds_read_b128 v[98:101], v80
	v_mfma_f32_16x16x32_bf16 v[36:39], v[94:97], v[106:109], v[36:39]
	ds_read_b128 v[102:105], v139 offset:18432
	ds_read_b128 v[106:109], v139 offset:20480
	v_mfma_f32_16x16x32_bf16 v[28:31], v[94:97], v[110:113], v[28:31]
	ds_read_b128 v[94:97], v139 offset:16384
	ds_read_b128 v[110:113], v139 offset:22528
	s_waitcnt lgkmcnt(0)
	v_mfma_f32_16x16x32_bf16 v[76:79], v[98:101], v[94:97], v[76:79]
	v_mfma_f32_16x16x32_bf16 v[72:75], v[98:101], v[102:105], v[72:75]
	v_mfma_f32_16x16x32_bf16 v[68:71], v[98:101], v[106:109], v[68:71]
	v_mfma_f32_16x16x32_bf16 v[64:67], v[98:101], v[110:113], v[64:67]
	ds_read_b128 v[98:101], v80 offset:2048
	s_waitcnt lgkmcnt(0)
	v_mfma_f32_16x16x32_bf16 v[60:63], v[98:101], v[94:97], v[60:63]
	v_mfma_f32_16x16x32_bf16 v[56:59], v[98:101], v[102:105], v[56:59]
	v_mfma_f32_16x16x32_bf16 v[52:55], v[98:101], v[106:109], v[52:55]
	v_mfma_f32_16x16x32_bf16 v[48:51], v[98:101], v[110:113], v[48:51]
	ds_read_b128 v[98:101], v80 offset:4096
	s_waitcnt lgkmcnt(0)
	v_mfma_f32_16x16x32_bf16 v[44:47], v[98:101], v[94:97], v[44:47]
	v_mfma_f32_16x16x32_bf16 v[40:43], v[98:101], v[102:105], v[40:43]
	v_mfma_f32_16x16x32_bf16 v[32:35], v[98:101], v[106:109], v[32:35]
	v_mfma_f32_16x16x32_bf16 v[24:27], v[98:101], v[110:113], v[24:27]
	ds_read_b128 v[98:101], v80 offset:6144
	s_sub_u32 vcc_lo, s26, 0x480
	s_cmpk_gt_u32 vcc_lo, 0x280
	s_cbranch_scc1 .Lg2_mid_done
	s_lshr_b32 vcc_lo, vcc_lo, 5
	s_mov_b64 s[100:101], exec
	s_mov_b64 exec, s[38:39]
	s_cbranch_execz .Lg2_mid_rest
	v_mov_b32_e32 v190, 0
	v_mov_b32_e32 v191, vcc_lo
	s_cmp_lg_u32 vcc_lo, 0
	s_cbranch_scc1 .Lg2_mid_chk
	v_mov_b32_e32 v192, 0
.Lg2_mid_chk:
	v_lshrrev_b32_e32 v189, v191, v192
	v_and_b32_e32 v189, 15, v189
	v_cmp_lt_u32_e32 vcc, 0, v189
	s_cbranch_vccnz .Lg2_mid_rest
.Lg2_mid_spin:
	global_load_dword v192, v[176:177], off offset:8 sc1
	s_waitcnt vmcnt(0)
	v_lshrrev_b32_e32 v189, v191, v192
	v_and_b32_e32 v189, 15, v189
	v_cmp_lt_u32_e32 vcc, 0, v189
	s_cbranch_vccnz .Lg2_mid_rest
	v_add_u32_e32 v190, 1, v190
	v_cmp_lt_u32_e32 vcc, 0x80000, v190
	s_cbranch_vccnz .Lg2_mid_rest
	s_sleep 1
	s_branch .Lg2_mid_spin
